# as previous (folded weight conversion) plus a guard: folding only on the 256-workgroup grid, otherwise the original conversion loop runs
# baseline (speedup 1.0000x reference)
.LBB0_127:
	v_readlane_b32 s22, v242, 62
	s_and_b32 s40, s22, 3
	s_cmp_lg_u32 s40, 0
	s_cbranch_scc1 .Lcvf_rows
	s_lshr_b32 s22, s22, 2
	s_mov_b32 s41, -1
	s_cmp_gt_i32 s38, 2
	s_cbranch_scc1 .Lcvf_a_done
	s_cmp_lg_u32 s87, 0x100
	s_cbranch_scc1 .Lcvf_a_done
	v_readlane_b32 s40, v243, 0
	v_readlane_b32 s42, v242, 50
	s_lshl_b32 s40, s40, 3
	s_add_i32 s40, s40, s42
	s_mul_i32 s42, s22, s86
	s_add_i32 s40, s40, s42
	s_cmp_ge_i32 s40, 0x1800
	s_cbranch_scc1 .Lcvf_a_done
	s_add_i32 s22, s38, 1
	v_readlane_b32 s48, v242, 44
	v_readlane_b32 s49, v242, 45
	s_cmp_ge_i32 s40, 0x1080
	s_cbranch_scc1 .Lcvf_win
	s_cmp_ge_i32 s40, 0xb00
	s_cbranch_scc1 .Lcvf_down
	s_mov_b32 s41, 1
	v_readlane_b32 s46, v242, 2
	v_readlane_b32 s47, v242, 3
	s_cmp_ge_i32 s40, 0x580
	s_cbranch_scc0 .Lcvf_gu
	s_mov_b32 s41, 2
	s_add_i32 s40, s40, 0xfffffa80
	v_readlane_b32 s46, v242, 4
	v_readlane_b32 s47, v242, 5

.LBB0_150:
	s_cmp_gt_i32 s38, 2
	s_cselect_b64 s[0:1], -1, 0
	s_cmpk_gt_i32 s2, 0x17ff
	s_cselect_b64 s[4:5], -1, 0
	s_or_b64 s[0:1], s[0:1], s[4:5]
	s_and_b64 vcc, exec, s[0:1]
	s_cmp_eq_u32 s87, 0x100
	s_cbranch_scc1 .LBB0_172
	s_cbranch_vccnz .LBB0_172
	s_add_i32 s0, s38, 1
	s_mov_b32 s78, s38
	s_lshl_b32 s4, s0, 10
	v_readlane_b32 s36, v243, 62
	s_mul_i32 s6, s0, 0xf00000
	s_ashr_i32 s5, s4, 31
	v_readlane_b32 s48, v242, 10
	s_mul_hi_i32 s1, s0, 0xf00000
	s_mul_hi_i32 s13, s0, 0xb00000
	s_mul_i32 s12, s0, 0xb00000
	v_readlane_b32 s49, v242, 11
	s_add_u32 s0, s48, s6
	v_readlane_b32 s46, v242, 8
	s_addc_u32 s1, s49, s1
	s_lshl_b64 s[10:11], s[4:5], 2
	v_readlane_b32 s47, v242, 9
	s_add_u32 s4, s46, s10
	v_readlane_b32 s44, v242, 6
	s_addc_u32 s5, s47, s11
	v_readlane_b32 s45, v242, 7
	s_add_u32 s6, s44, s12
	v_readlane_b32 s42, v242, 4
	s_addc_u32 s7, s45, s13
	v_readlane_b32 s43, v242, 5
	s_add_u32 s8, s42, s12
	v_readlane_b32 s38, v242, 0
	s_addc_u32 s9, s43, s13
	v_readlane_b32 s39, v242, 1
	s_add_u32 s10, s38, s10
	v_readlane_b32 s40, v242, 2
	s_addc_u32 s11, s39, s11
	v_readlane_b32 s41, v242, 3
	s_add_u32 s12, s40, s12
	s_addc_u32 s13, s41, s13
	s_lshl_b32 s14, s2, 1
	s_lshl_b32 s16, s2, 5
	s_lshl_b32 s17, s86, 5
	s_lshl_b32 s18, s2, 6
	s_lshl_b32 s19, s86, 6
	s_add_i32 s20, s14, 0x1ea00
	s_lshl_b32 s21, s86, 1
	s_mov_b32 s22, s2
	v_readlane_b32 s37, v243, 63
	v_readlane_b32 s50, v242, 12
	v_readlane_b32 s51, v242, 13
	s_branch .LBB0_154
